# pooling/kv phase item lists re-balanced around the 64 left-over in-proj tiles: items 0..959 on workgroups 64..255 (stride 192), items 960..2147 on all 256
# speedup vs baseline: 1.0147x; 1.0109x over previous
; __device__ __forceinline__ void run_phase(const Params& p, int ph, LAS unsigned char* lds, const int tid, const int bid) {
;     ...
;     } else if (sub == 1) { if (PH_MASK & 4)
;         for (int it = bid; it < 1024 + 544 + 580; it += G) {
;             if (it < 1024) sample_ret_unit(p, l, it, lds, tid);
;             else if (it < 1568) kv_unit(p, it - 1024, lds, tid);
;             else pool_item(p, l, it - 1568, tid);
;         }
.Lz1_p2go:
	s_cmpk_gt_i32 s82, 0x863
	s_cbranch_scc1 .LBB0_546
	v_readlane_b32 s0, v254, 46
	v_readlane_b32 s1, v254, 47
	s_mov_b32 s1, s91
	v_readlane_b32 s8, v253, 57
	s_lshl_b64 s[22:23], s[0:1], 7
	s_lshl_b64 s[24:25], s[0:1], 2
	s_lshl_b64 s[26:27], s[0:1], 10
	s_mov_b32 s6, s0
	s_lshl_b64 s[0:1], s[0:1], 13
	v_readlane_b32 s10, v253, 59
	v_readlane_b32 s11, v253, 60
	s_add_u32 s34, s10, s0
	v_writelane_b32 v254, s6, 46
	s_addc_u32 s35, s11, s1
	s_mov_b32 s38, s82
	s_cmpk_lg_u32 s42, 0x100
	s_cbranch_scc1 .Lp2_fwd0
	s_bitcmp1_b32 s82, 3
	s_cbranch_scc1 .Lz2_ibwd
	s_mov_b32 s0, 0
	s_add_i32 s38, s82, 0xffffffc0
	s_cmpk_gt_u32 s82, 63
	s_cbranch_scc1 .Lz2_iset
	s_mov_b32 s0, 1
	s_add_i32 s38, s82, 0x3c0
	s_branch .Lz2_iset
.Lz2_ibwd:
	s_mov_b32 s0, 1
	s_sub_i32 s38, 0x4a3, s82
	s_andn2_b32 s38, s38, 0xff
	s_add_i32 s38, s38, s82
	s_add_i32 s38, s38, 0x3c0
.Lz2_iset:
	s_nop 0
	v_writelane_b32 v255, s0, 9

; __device__ __forceinline__ void run_phase(const Params& p, int ph, LAS unsigned char* lds, const int tid, const int bid) {
;     ...
;         for (int it = bid; it < 1024 + 544 + 580; it += G) {
.LBB0_451:
	s_cmpk_lg_u32 s42, 0x100
	s_cbranch_scc1 .Lz2_generic
	v_readlane_b32 s1, v255, 9
	s_bitcmp1_b32 s82, 3
	s_cbranch_scc1 .Lz2_lbwd
	s_cmp_eq_u32 s1, 0
	s_cbranch_scc0 .Lz2_fB
	s_addk_i32 s38, 0xc0
	s_cmpk_lt_i32 s38, 0x3c0
	s_cbranch_scc1 .Lz2_lset
	s_mov_b32 s1, 1
	s_nop 0
	v_writelane_b32 v255, s1, 9
	s_add_i32 s38, s82, 0x3c0
	s_branch .Lz2_lset
.Lz2_fB:
	s_addk_i32 s38, 0x100
	s_cmpk_gt_i32 s38, 0x863
	s_cbranch_scc1 .LBB0_546
	s_branch .Lz2_lset
.Lz2_lbwd:
	s_cmp_eq_u32 s1, 0
	s_cbranch_scc1 .Lz2_bA
	s_addk_i32 s38, 0xff00
	s_cmpk_ge_i32 s38, 0x3c0
	s_cbranch_scc1 .Lz2_lset
	s_cmpk_lt_u32 s82, 64
	s_cbranch_scc1 .LBB0_546
	s_mov_b32 s1, 0
	s_nop 0
	v_writelane_b32 v255, s1, 9
	s_add_i32 s38, s82, 0x2c0
	s_branch .Lz2_lset
.Lz2_bA:
	s_addk_i32 s38, 0xff40
	s_cmp_lt_i32 s38, 0
	s_cbranch_scc1 .LBB0_546
.Lz2_lset:
	s_lshl_b32 s0, s38, 4
	s_add_i32 s36, s0, 0xffff9e00
	s_add_i32 s37, s0, 0xffff9dff
	s_branch .LBB0_452
